# P2: column tiles permuted so the 60 critical (5-unit) workgroups only get cheap-epilogue tiles; activation tiles go to workgroups with slack
# speedup vs baseline: 1.0136x; 1.0007x over previous
;     __device__ __forceinline__ bool decode(int L, Unit& u) const {
;     ...
;         int wgid = L; { const int q = nwg / NXCD, r = nwg % NXCD, xcd = wgid % NXCD, off = wgid / NXCD; wgid = (xcd < r ? xcd * (q + 1) : r * (q + 1) + (xcd - r) * q) + off; }
;         const int nig = WGM * nN, gid = wgid / nig, fm = gid * WGM, gsz = (nMt - fm) < WGM ? (nMt - fm) : WGM;
;         const int pmt = fm + ((wgid % nig) % gsz); u.pn = (wgid % nig) / gsz; u.bz = pmt / nMb; u.pm = pmt % nMb; return true;
.LBB0_222:
	s_and_b64 vcc, exec, s[16:17]
	s_cbranch_vccz .LBB0_224
	s_ashr_i32 s2, s88, 31
	s_lshr_b32 s2, s2, 29
	s_add_i32 s2, s88, s2
	s_ashr_i32 s3, s2, 3
	s_and_b32 s2, s2, -8
	s_sub_i32 s2, s88, s2
	s_cmp_lt_i32 s2, 0
	s_movk_i32 s4, 0x85
	s_cselect_b32 s4, s4, 0x84
	s_mul_i32 s2, s2, s4
	s_add_i32 s2, s2, s3
	s_mul_hi_i32 s3, s2, 0x3e0f83e1
	s_lshr_b32 s4, s3, 31
	s_ashr_i32 s3, s3, 6
	s_add_i32 s3, s3, s4
	s_lshl_b32 s4, s3, 3
	s_mulk_i32 s3, 0x108
	s_sub_i32 s2, s2, s3
	s_sext_i32_i16 s3, s2
	s_bfe_u32 s3, s3, 0x3001c
	s_add_i32 s3, s2, s3
	s_sext_i32_i16 s5, s3
	s_and_b32 s3, s3, 0xfff8
	s_sub_i32 s2, s2, s3
	s_sext_i32_i16 s2, s2
	s_add_i32 s2, s4, s2
	s_ashr_i32 s3, s2, 31
	s_lshr_b32 s3, s3, 27
	s_add_i32 s3, s2, s3
	s_andn2_b32 s3, s3, 31
	s_ashr_i32 s26, s5, 3
	s_sub_i32 s2, s2, s3
	s_cmp_gt_u32 s26, 31
	s_cbranch_scc1 .Lp2sga_done
	s_and_b32 s3, s26, 3
	s_cmp_lg_u32 s3, 0
	s_cbranch_scc1 .Lp2sga_1
	s_lshr_b32 s26, s26, 2
	s_branch .Lp2sga_done
.Lp2sga_1:
	s_cmp_lt_u32 s26, 17
	s_cbranch_scc1 .Lp2sga_2
	s_cmp_lg_u32 s3, 1
	s_cbranch_scc1 .Lp2sga_2
	s_sub_u32 s26, s26, 17
	s_lshr_b32 s26, s26, 2
	s_add_u32 s26, s26, 12
	s_branch .Lp2sga_done
.Lp2sga_2:
	s_cmp_gt_u32 s26, 15
	s_cbranch_scc1 .Lp2sga_3
	s_lshr_b32 s5, s26, 2
	s_sub_u32 s26, s26, s5
	s_sub_u32 s26, s26, 1
	s_branch .Lp2sga_4
.Lp2sga_3:
	s_sub_u32 s5, s26, 16
	s_lshr_b32 s5, s5, 2
	s_lshl_b32 s5, s5, 1
	s_add_u32 s26, s5, s3
	s_add_u32 s26, s26, 10
.Lp2sga_4:
	s_cmp_lt_u32 s26, 4
	s_cselect_b32 s5, 8, 12
	s_add_u32 s26, s26, s5

;     __device__ __forceinline__ bool decode(int L, Unit& u) const {
;     ...
;         int wgid = L; { const int q = nwg / NXCD, r = nwg % NXCD, xcd = wgid % NXCD, off = wgid / NXCD; wgid = (xcd < r ? xcd * (q + 1) : r * (q + 1) + (xcd - r) * q) + off; }
;         const int nig = WGM * nN, gid = wgid / nig, fm = gid * WGM, gsz = (nMt - fm) < WGM ? (nMt - fm) : WGM;
;         const int pmt = fm + ((wgid % nig) % gsz); u.pn = (wgid % nig) / gsz; u.bz = pmt / nMb; u.pm = pmt % nMb; return true;
.LBB0_233:
	s_andn2_b64 vcc, exec, s[30:31]
	s_cbranch_vccnz .LBB0_235
	s_ashr_i32 s22, s3, 31
	s_lshr_b32 s22, s22, 29
	s_add_i32 s22, s3, s22
	s_ashr_i32 s23, s22, 3
	s_and_b32 s22, s22, -8
	s_sub_i32 s3, s3, s22
	s_cmp_lt_i32 s3, 0
	s_movk_i32 s22, 0x85
	s_cselect_b32 s22, s22, 0x84
	s_mul_i32 s3, s3, s22
	s_add_i32 s3, s3, s23
	s_mul_hi_i32 s22, s3, 0x3e0f83e1
	s_lshr_b32 s23, s22, 31
	s_ashr_i32 s22, s22, 6
	s_add_i32 s22, s22, s23
	s_lshl_b32 s23, s22, 3
	s_mulk_i32 s22, 0x108
	s_sub_i32 s3, s3, s22
	s_bfe_u32 s22, s3, 0x3001c
	s_add_i32 s22, s3, s22
	s_sext_i32_i16 s24, s22
	s_and_b32 s22, s22, 0xfff8
	s_sub_i32 s3, s3, s22
	s_sext_i32_i16 s3, s3
	s_add_i32 s3, s23, s3
	s_ashr_i32 s23, s3, 31
	s_lshr_b32 s23, s23, 27
	s_add_i32 s23, s3, s23
	s_andn2_b32 s23, s23, 31
	s_ashr_i32 s22, s24, 3
	s_sub_i32 s24, s3, s23
	s_cmp_gt_u32 s22, 31
	s_cbranch_scc1 .Lp2sgb_done
	s_and_b32 s23, s22, 3
	s_cmp_lg_u32 s23, 0
	s_cbranch_scc1 .Lp2sgb_1
	s_lshr_b32 s22, s22, 2
	s_branch .Lp2sgb_done
.Lp2sgb_1:
	s_cmp_lt_u32 s22, 17
	s_cbranch_scc1 .Lp2sgb_2
	s_cmp_lg_u32 s23, 1
	s_cbranch_scc1 .Lp2sgb_2
	s_sub_u32 s22, s22, 17
	s_lshr_b32 s22, s22, 2
	s_add_u32 s22, s22, 12
	s_branch .Lp2sgb_done
.Lp2sgb_2:
	s_cmp_gt_u32 s22, 15
	s_cbranch_scc1 .Lp2sgb_3
	s_lshr_b32 s25, s22, 2
	s_sub_u32 s22, s22, s25
	s_sub_u32 s22, s22, 1
	s_branch .Lp2sgb_4
.Lp2sgb_3:
	s_sub_u32 s25, s22, 16
	s_lshr_b32 s25, s25, 2
	s_lshl_b32 s25, s25, 1
	s_add_u32 s22, s25, s23
	s_add_u32 s22, s22, 10
.Lp2sgb_4:
	s_cmp_lt_u32 s22, 4
	s_cselect_b32 s25, 8, 12
	s_add_u32 s22, s22, s25
